# gu SwiGLU epilogue: 8 elements batched per store, packed f32 mul/add (bit-identical math), no per-element dependent chains
# speedup vs baseline: 1.0031x; 1.0031x over previous
.LBB0_172:
	s_mov_b32 s100, 0xbfb8aa3b
	v_pk_mul_f32 v[156:157], v[126:127], s[100:101] op_sel_hi:[1,0]
	v_pk_mul_f32 v[158:159], v[128:129], s[100:101] op_sel_hi:[1,0]
	v_pk_mul_f32 v[160:161], v[118:119], s[100:101] op_sel_hi:[1,0]
	v_pk_mul_f32 v[162:163], v[120:121], s[100:101] op_sel_hi:[1,0]
	v_exp_f32_e32 v156, v156
	v_exp_f32_e32 v157, v157
	v_exp_f32_e32 v158, v158
	v_exp_f32_e32 v159, v159
	v_exp_f32_e32 v160, v160
	v_exp_f32_e32 v161, v161
	v_exp_f32_e32 v162, v162
	v_exp_f32_e32 v163, v163
	v_pk_add_f32 v[156:157], v[156:157], 1.0 op_sel_hi:[1,0]
	v_pk_add_f32 v[158:159], v[158:159], 1.0 op_sel_hi:[1,0]
	v_pk_add_f32 v[160:161], v[160:161], 1.0 op_sel_hi:[1,0]
	v_pk_add_f32 v[162:163], v[162:163], 1.0 op_sel_hi:[1,0]
	v_rcp_f32_e32 v156, v156
	v_rcp_f32_e32 v157, v157
	v_rcp_f32_e32 v158, v158
	v_rcp_f32_e32 v159, v159
	v_rcp_f32_e32 v160, v160
	v_rcp_f32_e32 v161, v161
	v_rcp_f32_e32 v162, v162
	v_rcp_f32_e32 v163, v163
	v_pk_mul_f32 v[156:157], v[126:127], v[156:157]
	v_pk_mul_f32 v[158:159], v[128:129], v[158:159]
	v_pk_mul_f32 v[160:161], v[118:119], v[160:161]
	v_pk_mul_f32 v[162:163], v[120:121], v[162:163]
	v_pk_mul_f32 v[156:157], v[156:157], v[122:123]
	v_pk_mul_f32 v[158:159], v[158:159], v[124:125]
	v_pk_mul_f32 v[160:161], v[160:161], v[114:115]
	v_pk_mul_f32 v[162:163], v[162:163], v[116:117]
	v_lshl_or_b32 v150, s24, 7, v147
	v_lshl_add_u32 v149, s30, 8, v1
	v_ashrrev_i32_e32 v151, 31, v150
	v_mov_b64_e32 v[144:145], s[66:67]
	v_mad_i64_i32 v[152:153], s[24:25], v149, s3, v[144:145]
	s_andn2_b64 vcc, exec, s[0:1]
	v_cvt_pk_bf16_f32 v116, v156, v157
	v_lshlrev_b64 v[114:115], 1, v[150:151]
	v_lshl_add_u64 v[120:121], v[152:153], 0, v[114:115]
	v_cvt_pk_bf16_f32 v117, v158, v159
	v_cvt_pk_bf16_f32 v118, v160, v161
	v_cvt_pk_bf16_f32 v119, v162, v163
	global_store_dwordx4 v[120:121], v[116:119], off
	v_pk_mul_f32 v[156:157], v[110:111], s[100:101] op_sel_hi:[1,0]
	v_pk_mul_f32 v[158:159], v[112:113], s[100:101] op_sel_hi:[1,0]
	v_pk_mul_f32 v[160:161], v[102:103], s[100:101] op_sel_hi:[1,0]
	v_pk_mul_f32 v[162:163], v[104:105], s[100:101] op_sel_hi:[1,0]
	v_exp_f32_e32 v156, v156
	v_exp_f32_e32 v157, v157
	v_exp_f32_e32 v158, v158
	v_exp_f32_e32 v159, v159
	v_exp_f32_e32 v160, v160
	v_exp_f32_e32 v161, v161
	v_exp_f32_e32 v162, v162
	v_exp_f32_e32 v163, v163
	v_pk_add_f32 v[156:157], v[156:157], 1.0 op_sel_hi:[1,0]
	v_pk_add_f32 v[158:159], v[158:159], 1.0 op_sel_hi:[1,0]
	v_pk_add_f32 v[160:161], v[160:161], 1.0 op_sel_hi:[1,0]
	v_pk_add_f32 v[162:163], v[162:163], 1.0 op_sel_hi:[1,0]
	v_rcp_f32_e32 v156, v156
	v_rcp_f32_e32 v157, v157
	v_rcp_f32_e32 v158, v158
	v_rcp_f32_e32 v159, v159
	v_rcp_f32_e32 v160, v160
	v_rcp_f32_e32 v161, v161
	v_rcp_f32_e32 v162, v162
	v_rcp_f32_e32 v163, v163
	v_pk_mul_f32 v[156:157], v[110:111], v[156:157]
	v_pk_mul_f32 v[158:159], v[112:113], v[158:159]
	v_pk_mul_f32 v[160:161], v[102:103], v[160:161]
	v_pk_mul_f32 v[162:163], v[104:105], v[162:163]
	v_pk_mul_f32 v[156:157], v[156:157], v[106:107]
	v_pk_mul_f32 v[158:159], v[158:159], v[108:109]
	v_pk_mul_f32 v[160:161], v[160:161], v[98:99]
	v_pk_mul_f32 v[162:163], v[162:163], v[100:101]
	v_or_b32_e32 v116, 16, v149
	v_mad_i64_i32 v[116:117], s[24:25], v116, s3, v[144:145]
	v_lshl_add_u64 v[102:103], v[116:117], 0, v[114:115]
	v_cvt_pk_bf16_f32 v98, v156, v157
	v_cvt_pk_bf16_f32 v99, v158, v159
	v_cvt_pk_bf16_f32 v100, v160, v161
	v_cvt_pk_bf16_f32 v101, v162, v163
	global_store_dwordx4 v[102:103], v[98:101], off
	v_pk_mul_f32 v[156:157], v[94:95], s[100:101] op_sel_hi:[1,0]
	v_pk_mul_f32 v[158:159], v[96:97], s[100:101] op_sel_hi:[1,0]
	v_pk_mul_f32 v[160:161], v[86:87], s[100:101] op_sel_hi:[1,0]
	v_pk_mul_f32 v[162:163], v[88:89], s[100:101] op_sel_hi:[1,0]
	v_exp_f32_e32 v156, v156
	v_exp_f32_e32 v157, v157
	v_exp_f32_e32 v158, v158
	v_exp_f32_e32 v159, v159
	v_exp_f32_e32 v160, v160
	v_exp_f32_e32 v161, v161
	v_exp_f32_e32 v162, v162
	v_exp_f32_e32 v163, v163
	v_pk_add_f32 v[156:157], v[156:157], 1.0 op_sel_hi:[1,0]
	v_pk_add_f32 v[158:159], v[158:159], 1.0 op_sel_hi:[1,0]
	v_pk_add_f32 v[160:161], v[160:161], 1.0 op_sel_hi:[1,0]
	v_pk_add_f32 v[162:163], v[162:163], 1.0 op_sel_hi:[1,0]
	v_rcp_f32_e32 v156, v156
	v_rcp_f32_e32 v157, v157
	v_rcp_f32_e32 v158, v158
	v_rcp_f32_e32 v159, v159
	v_rcp_f32_e32 v160, v160
	v_rcp_f32_e32 v161, v161
	v_rcp_f32_e32 v162, v162
	v_rcp_f32_e32 v163, v163
	v_pk_mul_f32 v[156:157], v[94:95], v[156:157]
	v_pk_mul_f32 v[158:159], v[96:97], v[158:159]
	v_pk_mul_f32 v[160:161], v[86:87], v[160:161]
	v_pk_mul_f32 v[162:163], v[88:89], v[162:163]
	v_pk_mul_f32 v[156:157], v[156:157], v[90:91]
	v_pk_mul_f32 v[158:159], v[158:159], v[92:93]
	v_pk_mul_f32 v[160:161], v[160:161], v[82:83]
	v_pk_mul_f32 v[162:163], v[162:163], v[84:85]
	v_or_b32_e32 v98, 32, v149
	v_mad_i64_i32 v[98:99], s[24:25], v98, s3, v[144:145]
	v_lshl_add_u64 v[86:87], v[98:99], 0, v[114:115]
	v_cvt_pk_bf16_f32 v82, v156, v157
	v_cvt_pk_bf16_f32 v83, v158, v159
	v_cvt_pk_bf16_f32 v84, v160, v161
	v_cvt_pk_bf16_f32 v85, v162, v163
	global_store_dwordx4 v[86:87], v[82:85], off
	v_pk_mul_f32 v[156:157], v[78:79], s[100:101] op_sel_hi:[1,0]
	v_pk_mul_f32 v[158:159], v[80:81], s[100:101] op_sel_hi:[1,0]
	v_pk_mul_f32 v[160:161], v[70:71], s[100:101] op_sel_hi:[1,0]
	v_pk_mul_f32 v[162:163], v[72:73], s[100:101] op_sel_hi:[1,0]
	v_exp_f32_e32 v156, v156
	v_exp_f32_e32 v157, v157
	v_exp_f32_e32 v158, v158
	v_exp_f32_e32 v159, v159
	v_exp_f32_e32 v160, v160
	v_exp_f32_e32 v161, v161
	v_exp_f32_e32 v162, v162
	v_exp_f32_e32 v163, v163
	v_pk_add_f32 v[156:157], v[156:157], 1.0 op_sel_hi:[1,0]
	v_pk_add_f32 v[158:159], v[158:159], 1.0 op_sel_hi:[1,0]
	v_pk_add_f32 v[160:161], v[160:161], 1.0 op_sel_hi:[1,0]
	v_pk_add_f32 v[162:163], v[162:163], 1.0 op_sel_hi:[1,0]
	v_rcp_f32_e32 v156, v156
	v_rcp_f32_e32 v157, v157
	v_rcp_f32_e32 v158, v158
	v_rcp_f32_e32 v159, v159
	v_rcp_f32_e32 v160, v160
	v_rcp_f32_e32 v161, v161
	v_rcp_f32_e32 v162, v162
	v_rcp_f32_e32 v163, v163
	v_pk_mul_f32 v[156:157], v[78:79], v[156:157]
	v_pk_mul_f32 v[158:159], v[80:81], v[158:159]
	v_pk_mul_f32 v[160:161], v[70:71], v[160:161]
	v_pk_mul_f32 v[162:163], v[72:73], v[162:163]
	v_pk_mul_f32 v[156:157], v[156:157], v[74:75]
	v_pk_mul_f32 v[158:159], v[158:159], v[76:77]
	v_pk_mul_f32 v[160:161], v[160:161], v[66:67]
	v_pk_mul_f32 v[162:163], v[162:163], v[68:69]
	v_or_b32_e32 v82, 48, v149
	v_mad_i64_i32 v[82:83], s[24:25], v82, s3, v[144:145]
	v_lshl_add_u64 v[70:71], v[82:83], 0, v[114:115]
	v_cvt_pk_bf16_f32 v66, v156, v157
	v_cvt_pk_bf16_f32 v67, v158, v159
	v_cvt_pk_bf16_f32 v68, v160, v161
	v_cvt_pk_bf16_f32 v69, v162, v163
	global_store_dwordx4 v[70:71], v[66:69], off
	v_pk_mul_f32 v[156:157], v[62:63], s[100:101] op_sel_hi:[1,0]
	v_pk_mul_f32 v[158:159], v[64:65], s[100:101] op_sel_hi:[1,0]
	v_pk_mul_f32 v[160:161], v[54:55], s[100:101] op_sel_hi:[1,0]
	v_pk_mul_f32 v[162:163], v[56:57], s[100:101] op_sel_hi:[1,0]
	v_exp_f32_e32 v156, v156
	v_exp_f32_e32 v157, v157
	v_exp_f32_e32 v158, v158
	v_exp_f32_e32 v159, v159
	v_exp_f32_e32 v160, v160
	v_exp_f32_e32 v161, v161
	v_exp_f32_e32 v162, v162
	v_exp_f32_e32 v163, v163
	v_pk_add_f32 v[156:157], v[156:157], 1.0 op_sel_hi:[1,0]
	v_pk_add_f32 v[158:159], v[158:159], 1.0 op_sel_hi:[1,0]
	v_pk_add_f32 v[160:161], v[160:161], 1.0 op_sel_hi:[1,0]
	v_pk_add_f32 v[162:163], v[162:163], 1.0 op_sel_hi:[1,0]
	v_rcp_f32_e32 v156, v156
	v_rcp_f32_e32 v157, v157
	v_rcp_f32_e32 v158, v158
	v_rcp_f32_e32 v159, v159
	v_rcp_f32_e32 v160, v160
	v_rcp_f32_e32 v161, v161
	v_rcp_f32_e32 v162, v162
	v_rcp_f32_e32 v163, v163
	v_pk_mul_f32 v[156:157], v[62:63], v[156:157]
	v_pk_mul_f32 v[158:159], v[64:65], v[158:159]
	v_pk_mul_f32 v[160:161], v[54:55], v[160:161]
	v_pk_mul_f32 v[162:163], v[56:57], v[162:163]
	v_pk_mul_f32 v[156:157], v[156:157], v[58:59]
	v_pk_mul_f32 v[158:159], v[158:159], v[60:61]
	v_pk_mul_f32 v[160:161], v[160:161], v[50:51]
	v_pk_mul_f32 v[162:163], v[162:163], v[52:53]
	v_add_u32_e32 v66, 0x80, v149
	v_mad_i64_i32 v[66:67], s[24:25], v66, s3, v[144:145]
	v_lshl_add_u64 v[54:55], v[66:67], 0, v[114:115]
	v_cvt_pk_bf16_f32 v50, v156, v157
	v_cvt_pk_bf16_f32 v51, v158, v159
	v_cvt_pk_bf16_f32 v52, v160, v161
	v_cvt_pk_bf16_f32 v53, v162, v163
	global_store_dwordx4 v[54:55], v[50:53], off
	v_pk_mul_f32 v[156:157], v[46:47], s[100:101] op_sel_hi:[1,0]
	v_pk_mul_f32 v[158:159], v[48:49], s[100:101] op_sel_hi:[1,0]
	v_pk_mul_f32 v[160:161], v[38:39], s[100:101] op_sel_hi:[1,0]
	v_pk_mul_f32 v[162:163], v[40:41], s[100:101] op_sel_hi:[1,0]
	v_exp_f32_e32 v156, v156
	v_exp_f32_e32 v157, v157
	v_exp_f32_e32 v158, v158
	v_exp_f32_e32 v159, v159
	v_exp_f32_e32 v160, v160
	v_exp_f32_e32 v161, v161
	v_exp_f32_e32 v162, v162
	v_exp_f32_e32 v163, v163
	v_pk_add_f32 v[156:157], v[156:157], 1.0 op_sel_hi:[1,0]
	v_pk_add_f32 v[158:159], v[158:159], 1.0 op_sel_hi:[1,0]
	v_pk_add_f32 v[160:161], v[160:161], 1.0 op_sel_hi:[1,0]
	v_pk_add_f32 v[162:163], v[162:163], 1.0 op_sel_hi:[1,0]
	v_rcp_f32_e32 v156, v156
	v_rcp_f32_e32 v157, v157
	v_rcp_f32_e32 v158, v158
	v_rcp_f32_e32 v159, v159
	v_rcp_f32_e32 v160, v160
	v_rcp_f32_e32 v161, v161
	v_rcp_f32_e32 v162, v162
	v_rcp_f32_e32 v163, v163
	v_pk_mul_f32 v[156:157], v[46:47], v[156:157]
	v_pk_mul_f32 v[158:159], v[48:49], v[158:159]
	v_pk_mul_f32 v[160:161], v[38:39], v[160:161]
	v_pk_mul_f32 v[162:163], v[40:41], v[162:163]
	v_pk_mul_f32 v[156:157], v[156:157], v[42:43]
	v_pk_mul_f32 v[158:159], v[158:159], v[44:45]
	v_pk_mul_f32 v[160:161], v[160:161], v[34:35]
	v_pk_mul_f32 v[162:163], v[162:163], v[36:37]
	v_add_u32_e32 v50, 0x90, v149
	v_mad_i64_i32 v[50:51], s[24:25], v50, s3, v[144:145]
	v_lshl_add_u64 v[38:39], v[50:51], 0, v[114:115]
	v_cvt_pk_bf16_f32 v34, v156, v157
	v_cvt_pk_bf16_f32 v35, v158, v159
	v_cvt_pk_bf16_f32 v36, v160, v161
	v_cvt_pk_bf16_f32 v37, v162, v163
	global_store_dwordx4 v[38:39], v[34:37], off
	v_pk_mul_f32 v[156:157], v[30:31], s[100:101] op_sel_hi:[1,0]
	v_pk_mul_f32 v[158:159], v[32:33], s[100:101] op_sel_hi:[1,0]
	v_pk_mul_f32 v[160:161], v[22:23], s[100:101] op_sel_hi:[1,0]
	v_pk_mul_f32 v[162:163], v[24:25], s[100:101] op_sel_hi:[1,0]
	v_exp_f32_e32 v156, v156
	v_exp_f32_e32 v157, v157
	v_exp_f32_e32 v158, v158
	v_exp_f32_e32 v159, v159
	v_exp_f32_e32 v160, v160
	v_exp_f32_e32 v161, v161
	v_exp_f32_e32 v162, v162
	v_exp_f32_e32 v163, v163
	v_pk_add_f32 v[156:157], v[156:157], 1.0 op_sel_hi:[1,0]
	v_pk_add_f32 v[158:159], v[158:159], 1.0 op_sel_hi:[1,0]
	v_pk_add_f32 v[160:161], v[160:161], 1.0 op_sel_hi:[1,0]
	v_pk_add_f32 v[162:163], v[162:163], 1.0 op_sel_hi:[1,0]
	v_rcp_f32_e32 v156, v156
	v_rcp_f32_e32 v157, v157
	v_rcp_f32_e32 v158, v158
	v_rcp_f32_e32 v159, v159
	v_rcp_f32_e32 v160, v160
	v_rcp_f32_e32 v161, v161
	v_rcp_f32_e32 v162, v162
	v_rcp_f32_e32 v163, v163
	v_pk_mul_f32 v[156:157], v[30:31], v[156:157]
	v_pk_mul_f32 v[158:159], v[32:33], v[158:159]
	v_pk_mul_f32 v[160:161], v[22:23], v[160:161]
	v_pk_mul_f32 v[162:163], v[24:25], v[162:163]
	v_pk_mul_f32 v[156:157], v[156:157], v[26:27]
	v_pk_mul_f32 v[158:159], v[158:159], v[28:29]
	v_pk_mul_f32 v[160:161], v[160:161], v[18:19]
	v_pk_mul_f32 v[162:163], v[162:163], v[20:21]
	v_add_u32_e32 v34, 0xa0, v149
	v_mad_i64_i32 v[34:35], s[24:25], v34, s3, v[144:145]
	v_lshl_add_u64 v[22:23], v[34:35], 0, v[114:115]
	v_cvt_pk_bf16_f32 v18, v156, v157
	v_cvt_pk_bf16_f32 v19, v158, v159
	v_cvt_pk_bf16_f32 v20, v160, v161
	v_cvt_pk_bf16_f32 v21, v162, v163
	global_store_dwordx4 v[22:23], v[18:21], off
	v_pk_mul_f32 v[156:157], v[14:15], s[100:101] op_sel_hi:[1,0]
	v_pk_mul_f32 v[158:159], v[16:17], s[100:101] op_sel_hi:[1,0]
	v_pk_mul_f32 v[160:161], v[6:7], s[100:101] op_sel_hi:[1,0]
	v_pk_mul_f32 v[162:163], v[8:9], s[100:101] op_sel_hi:[1,0]
	v_exp_f32_e32 v156, v156
	v_exp_f32_e32 v157, v157
	v_exp_f32_e32 v158, v158
	v_exp_f32_e32 v159, v159
	v_exp_f32_e32 v160, v160
	v_exp_f32_e32 v161, v161
	v_exp_f32_e32 v162, v162
	v_exp_f32_e32 v163, v163
	v_pk_add_f32 v[156:157], v[156:157], 1.0 op_sel_hi:[1,0]
	v_pk_add_f32 v[158:159], v[158:159], 1.0 op_sel_hi:[1,0]
	v_pk_add_f32 v[160:161], v[160:161], 1.0 op_sel_hi:[1,0]
	v_pk_add_f32 v[162:163], v[162:163], 1.0 op_sel_hi:[1,0]
	v_rcp_f32_e32 v156, v156
	v_rcp_f32_e32 v157, v157
	v_rcp_f32_e32 v158, v158
	v_rcp_f32_e32 v159, v159
	v_rcp_f32_e32 v160, v160
	v_rcp_f32_e32 v161, v161
	v_rcp_f32_e32 v162, v162
	v_rcp_f32_e32 v163, v163
	v_pk_mul_f32 v[156:157], v[14:15], v[156:157]
	v_pk_mul_f32 v[158:159], v[16:17], v[158:159]
	v_pk_mul_f32 v[160:161], v[6:7], v[160:161]
	v_pk_mul_f32 v[162:163], v[8:9], v[162:163]
	v_pk_mul_f32 v[156:157], v[156:157], v[10:11]
	v_pk_mul_f32 v[158:159], v[158:159], v[12:13]
	v_pk_mul_f32 v[160:161], v[160:161], v[2:3]
	v_pk_mul_f32 v[162:163], v[162:163], v[4:5]
	v_add_u32_e32 v18, 0xb0, v149
	v_mad_i64_i32 v[18:19], s[24:25], v18, s3, v[144:145]
	s_mov_b64 s[24:25], -1
	v_lshl_add_u64 v[6:7], v[18:19], 0, v[114:115]
	v_cvt_pk_bf16_f32 v2, v156, v157
	v_cvt_pk_bf16_f32 v3, v158, v159
	v_cvt_pk_bf16_f32 v4, v160, v161
	v_cvt_pk_bf16_f32 v5, v162, v163
	global_store_dwordx4 v[6:7], v[2:5], off
	s_cbranch_vccnz .LBB0_161
	s_andn2_b64 vcc, exec, s[6:7]
	s_cbranch_vccnz .LBB0_160
	s_barrier
	s_branch .LBB0_160
